# D attention units: one static s_setprio 1 for waves 0-3 instead of 4-7
# baseline (speedup 1.0000x reference)
; #define LAS __attribute__((address_space(3)))
; #define GAS __attribute__((address_space(1)))
; DI unsigned char* ARGWS(const Ctx& C) { return (unsigned char*)ARGP(C, 22); }
; DI void attn_unit_d32(const Ctx& C, const bf16_t* __restrict__ Z, bf16_t* __restrict__ Y, int b, int qsel, int hsel, bool ctxq, float lam, float post_scale, const float* subln, const float mref) {
;     constexpr int KST = 136, VST = 72, AT_VT = 64 * 136 * 2;
;     const int tid = C.tid, lane = C.lane, w = C.wave, l31 = lane & 31, hh = lane >> 5, sm = w >> 2, qg = w & 3;
;     const int qrow = (ctxq ? NLAT + 256 * b : b * SEQ) + 128 * qsel + 32 * qg + l31;
;     const int qcol = Z_DQ + 128 * hsel + 64 * sm, kcol = Z_DK + 128 * hsel, vcol = Z_DV + 128 * hsel, ycol = 1536 + 128 * hsel;
;     const int nt = ctxq ? 4 : 36;
;     LAS bf16_t* lds16 = (LAS bf16_t*)C.lds;
;     bf16x8 qf[4];
; #pragma unroll
;     for (int ks = 0; ks < 4; ++ks) qf[ks] = *(const GAS bf16x8*)(Z + (size_t)qrow * ZW + qcol + 16 * ks + 8 * hh);
;     const float negm = -mref;
;     f32x16 o[4]; float lsum = 0.f;
; #pragma unroll
;     for (int d = 0; d < 4; ++d)
; #pragma unroll
;         for (int r = 0; r < 16; ++r) o[d][r] = 0.f;
;     u32x4 kA[2], vA[2], kB[2], vB[2];
;     const int krow = tid >> 3, kch = tid & 7, vp2 = 2 * (lane & 31), vhs = lane >> 5;
;     ...
;     const unsigned koff = (unsigned)(krow * ZW + kcol + 8 * kch), voff = (unsigned)(vp2 * ZW + vcol + 8 * (2 * w + vhs));
; DI void phase_mixers(const Ctx& C, int l, bool last) {
;     unsigned char* ws = ARGWS(C);
;     const bf16_t* Z = (const bf16_t*)(ws + WS_Z); bf16_t* Y = (bf16_t*)(ws + WS_Y);
;     const float* misc = (const float*)(ws + WS_MISC);
;     const float lam = misc[l], post = misc[2 + l], mA = misc[8 + 4 * l], mB = misc[9 + 4 * l], mD = misc[10 + 4 * l];
;     const float* sink = ARGP(C, 11) + l * 8; const float* rpb = ARGP(C, 12) + (size_t)l * 8 * 15 * 31; const float* subln = ARGP(C, 16) + l * 128;
;     const bf16_t* cwT = (const bf16_t*)(ws + WS_CWT) + (size_t)l * 4 * 128 * 128; const float* cscale = ARGP(C, 14) + l * 512;
;     const int nC = last ? (NLAT / 64) * 4 : (MROWS / 64) * 4;
;     for (int rep = 0; rep < ((UDUP & 1) ? 2 : 1); ++rep)
;     if (UMASK & 1) for (int u = C.bid; u < 256; u += C.G) { const int b = u >> 6, qb = (u >> 2) & 15, h = u & 3; attn_unit_d32(C, Z, Y, b, qb, h, false, lam, post, subln, mD); }
.LBB0_391:
	s_andn2_b64 vcc, exec, s[0:1]
	s_cbranch_vccnz .LBB0_694
	s_ashr_i32 s85, s84, 31
	v_readlane_b32 s0, v248, 3
	s_cmp_lt_i32 s0, 2
	s_mov_b64 s[0:1], -1
	v_readlane_b32 s81, v249, 63
	v_readlane_b32 s60, v249, 59
	v_readlane_b32 s61, v249, 60
	s_cbranch_scc1 .LBB0_648
	v_readlane_b32 s0, v248, 3
	s_cmp_gt_i32 s0, 2
	s_mov_b64 s[0:1], -1
	s_cbranch_scc0 .LBB0_549
	v_mov_b32_e32 v0, s66
	ds_read_b32 v0, v0
	s_lshl_b32 s0, s84, 7
	s_ashr_i32 s1, s0, 31
	s_mul_i32 s7, s84, 12
	s_mul_hi_i32 s6, s84, 12
	s_waitcnt lgkmcnt(0)
	v_readfirstlane_b32 s30, v0
	v_mov_b32_e32 v0, s96
	ds_read_b32 v0, v0
	s_add_u32 s8, s30, 0x1b800000
	v_ashrrev_i32_e32 v177, 3, v208
	s_movk_i32 s47, 0x100
	s_movk_i32 s41, 0x2000
	s_waitcnt lgkmcnt(0)
	v_readfirstlane_b32 s31, v0
	s_addc_u32 s9, s31, 0
	s_add_u32 s10, s30, 0x17000000
	s_addc_u32 s11, s31, 0
	s_lshl_b64 s[4:5], s[84:85], 2
	s_add_u32 s4, s30, s4
	s_addc_u32 s5, s31, s5
	v_mov_b64_e32 v[2:3], s[4:5]
	s_add_u32 s4, s4, s7
	s_addc_u32 s5, s5, s6
	flat_load_dword v168, v[2:3]
	flat_load_dword v176, v[2:3] offset:8
	v_mov_b64_e32 v[2:3], s[4:5]
	flat_load_dwordx3 v[164:166], v[2:3] offset:32
	v_readlane_b32 s4, v249, 14
	v_readlane_b32 s5, v249, 19
	s_lshl_b64 s[0:1], s[0:1], 2
	v_mov_b32_e32 v0, s4
	ds_read_b32 v0, v0
	v_readlane_b32 s4, v249, 15
	s_mov_b32 s52, 0x3fb8aa3b
	v_readlane_b32 s58, v248, 2
	s_waitcnt lgkmcnt(0)
	v_readfirstlane_b32 s16, v0
	v_mov_b32_e32 v0, s4
	ds_read_b32 v0, v0
	v_readlane_b32 s4, v249, 16
	s_waitcnt lgkmcnt(0)
	v_readfirstlane_b32 s17, v0
	v_mov_b32_e32 v0, s4
	ds_read_b32 v0, v0
	v_readlane_b32 s4, v249, 17
	s_waitcnt lgkmcnt(0)
	v_readfirstlane_b32 s26, v0
	v_mov_b32_e32 v0, s4
	ds_read_b32 v0, v0
	v_readlane_b32 s4, v249, 18
	s_waitcnt lgkmcnt(0)
	v_readfirstlane_b32 s27, v0
	v_mov_b32_e32 v0, s4
	ds_read_b32 v0, v0
	s_waitcnt lgkmcnt(0)
	v_readfirstlane_b32 s4, v0
	v_mov_b32_e32 v0, s5
	ds_read_b32 v0, v0
	s_add_u32 s12, s4, s0
	v_readlane_b32 s0, v249, 20
	s_waitcnt lgkmcnt(0)
	v_readfirstlane_b32 s5, v0
	v_mov_b32_e32 v0, s0
	ds_read_b32 v0, v0
	v_readlane_b32 s0, v249, 21
	s_addc_u32 s13, s5, s1
	s_cmpk_lt_i32 s51, 0x100
	s_cselect_b64 s[4:5], -1, 0
	s_waitcnt lgkmcnt(0)
	v_readfirstlane_b32 s34, v0
	v_mov_b32_e32 v0, s0
	ds_read_b32 v0, v0
	s_movk_i32 s0, 0x1100
	s_cmpk_gt_i32 s51, 0xff
	v_mul_lo_u32 v178, v177, s0
	s_waitcnt lgkmcnt(0)
	v_readfirstlane_b32 s35, v0
	s_waitcnt vmcnt(0)
	v_mov_b32_e32 v169, v168
	v_xor_b32_e32 v4, 0x80000000, v166
	v_mov_b32_e32 v5, v4
	v_mov_b32_e32 v6, v4
	v_mov_b32_e32 v7, v4
	v_mov_b32_e32 v8, v4
	v_mov_b32_e32 v9, v4
	v_mov_b32_e32 v10, v4
	v_mov_b32_e32 v11, v4
	v_mov_b32_e32 v12, v4
	v_mov_b32_e32 v13, v4
	v_mov_b32_e32 v14, v4
	v_mov_b32_e32 v15, v4
	v_mov_b32_e32 v16, v4
	v_mov_b32_e32 v17, v4
	v_mov_b32_e32 v18, v4
	v_mov_b32_e32 v19, v4
	s_cbranch_scc1 .LBB0_412
	v_lshlrev_b32_e32 v21, 3, v206
	v_ashrrev_i32_e32 v20, 5, v206
	v_and_b32_e32 v21, 56, v21
	v_and_b32_e32 v0, 31, v206
	v_lshlrev_b32_e32 v2, 3, v20
	v_or_b32_e32 v22, v178, v21
	v_add_u32_e32 v179, 0xd00, v22
	v_mul_u32_u24_e32 v22, 0x2200, v0
	v_lshl_add_u32 v23, s58, 4, v2
	s_movk_i32 s6, 0xf00
	v_add3_u32 v180, v22, v23, s6
	s_movk_i32 s6, 0x110
	s_ashr_i32 s0, s58, 2
	v_mul_lo_u32 v22, v177, s6
	v_lshlrev_b32_e32 v21, 1, v21
	s_movk_i32 s6, 0x90
	s_lshl_b32 s1, s58, 5
	s_lshl_b32 s18, s0, 6
	v_add3_u32 v181, 0, v22, v21
	v_mul_lo_u32 v21, v23, s6
	s_lshl_b32 s6, s0, 7
	s_and_b32 s1, s1, 0x60
	s_add_i32 s19, s18, 0xb00
	s_add_i32 s6, s6, 0
	v_and_b32_e32 v22, 25, v0
	v_lshrrev_b32_e32 v182, 1, v0
	v_and_b32_e32 v182, 2, v182
	v_or_b32_e32 v22, v22, v182
	v_lshlrev_b32_e32 v182, 1, v0
	v_and_b32_e32 v182, 4, v182
	v_or_b32_e32 v22, v22, v182
	v_lshlrev_b32_e32 v22, 2, v22
	v_lshlrev_b32_e32 v183, 4, v20
	v_or_b32_e32 v187, s1, v0
	s_movk_i32 s1, 0x210
	s_cmp_eq_u32 s0, 1
	v_lshlrev_b32_e32 v166, 2, v20
	v_add3_u32 v182, 0, v21, v22
	v_add_u32_e32 v21, s6, v183
	v_mul_u32_u24_e32 v184, 0x110, v0
	v_add_u32_e32 v22, 0, v2
	v_mul_u32_u24_e32 v185, 0x90, v0
	v_lshlrev_b32_e32 v23, 2, v206
	v_mad_u32_u24 v0, v187, s1, 0
	s_cselect_b64 s[6:7], -1, 0
	s_cmp_lt_u32 s58, 4
	v_ashrrev_i32_e32 v167, 31, v166
	v_ashrrev_i32_e32 v3, 31, v2
	v_xor_b32_e32 v186, 0x80, v23
	s_cselect_b64 s[14:15], -1, 0
	v_lshl_add_u64 v[170:171], v[166:167], 2, s[12:13]
	v_add_u32_e32 v188, v21, v184
	v_add_u32_e32 v189, v183, v185
	v_add_u32_e32 v190, v0, v183
	v_readlane_b32 s100, v249, 53
	s_nop 3
	s_cmp_lt_u32 s100, 4
	s_cbranch_scc0 .Ldprio_done
	s_setprio 1
